# trimmed lane-swap S5 loop: the four XS fragment reads for the next chunk's y MFMAs are issued right after the current chunk's y store, so the loop head no longer exposes the LDS latency
# baseline (speedup 1.0000x reference)
; #define LAS __attribute__((address_space(3)))
; DI unsigned pk2(float lo, float hi) { f32x2 v = {lo, hi}; bf16x2_t b = __builtin_convertvector(v, bf16x2_t); return __builtin_bit_cast(unsigned, b); }
; #define MFMA16(a, b, c) __builtin_amdgcn_mfma_f32_16x16x32_bf16((a), (b), (c), 0, 0, 0)
; #define S5_CB() asm volatile("" ::: "memory")
; DI void s5_phase(const KArgs& a, int zz, int o, const bf16_t* H, bf16_t* YF, bf16_t* YB, LAS unsigned char* lds, int G, int bid, int wave, int lane) {
;     ...
;         auto iter = [&](const int ci, const bool do_c) __attribute__((always_inline)) {
;             const size_t row0 = chunk_row(ci);
;             const u32x4 u3 = loadu(ci + 3);
;             f32x2 bu[16];
; #pragma unroll
;             for (int s = 0; s < 16; ++s) { const int tt = DIRC ? 15 - s : s; bu[s] = *(const LAS f32x2*)(BU + tt * 132 + 2 * lane); }
;             bf16x8 Ax[4];
;             if (do_c) {
; #pragma unroll
;                 for (int kb = 0; kb < 4; ++kb) Ax[kb] = *(const LAS bf16x8*)(XS + fr * 68 + kb * 16 + fq * 4); }
;             S5_CB();
;             stageA(u1);
;             S5_CB();
; #pragma unroll
;             for (int s = 0; s < 16; ++s) { const int tt = DIRC ? 15 - s : s;
;                 const float nr = __builtin_fmaf(abr, xr, __builtin_fmaf(nabi, xi, bu[s][0])); const float ni = __builtin_fmaf(abr, xi, __builtin_fmaf(abi, xr, bu[s][1])); xr = nr; xi = ni;
;                 XS[tt * 68 + lane] = pk2(xr, xi); }
;             if (do_c) {
;                 f32x4 ya = (f32x4){0.f, 0.f, 0.f, 0.f};
; #pragma unroll
;                 for (int kb = 0; kb < 4; ++kb) ya = MFMA16(Cb[kb], Ax[kb], ya);
;                 u32x2 w; w.x = pk2(ya[0], ya[1]); w.y = pk2(ya[2], ya[3]); *(u32x2*)(Y + (rowprev + fr) * D + g * 16 + fq * 4) = w; }
;             S5_CB();
;             rowprev = row0; u1 = u2; u2 = u3;
;         };
;         iter(0, false);
;         for (int ci = 1; ci < 272; ++ci) iter(ci, true);
.Ls5f_bwd_entry:
	s_add_u32 s98, s58, 0xfb0
	s_addc_u32 s99, s59, 0
	s_mov_b32 s100, 0x20000
	s_mov_b32 s101, 0
	s_lshl_b64 s[98:99], s[98:99], 11
	v_lshlrev_b64 v[56:57], 11, v[104:105]
	v_lshl_add_u64 v[246:247], v[126:127], 0, v[56:57]
	v_lshl_add_u64 v[248:249], v[128:129], 0, v[56:57]
	v_lshl_add_u64 v[248:249], v[248:249], 0, s[100:101]
	s_mov_b32 s100, 17
	ds_read_b128 v[56:59], v148 offset:8448
	ds_read_b128 v[60:63], v148 offset:8512
	ds_read_b128 v[64:67], v148 offset:8576
	ds_read_b128 v[68:71], v148 offset:8640
.Ls5f_bwd_loop:
	s_waitcnt lgkmcnt(0)
	v_mfma_f32_16x16x32_bf16 v[56:59], v[32:35], v[56:59], 0
	v_mfma_f32_16x16x32_bf16 v[56:59], v[36:39], v[60:63], v[56:59]
	v_mfma_f32_16x16x32_bf16 v[56:59], v[40:43], v[64:67], v[56:59]
	v_mfma_f32_16x16x32_bf16 v[56:59], v[44:47], v[68:71], v[56:59]
	v_fma_f32 v60, -v125, v133, v241
	v_fma_f32 v61, v125, v132, v245
	v_fmac_f32_e32 v60, v122, v132
	v_fmac_f32_e32 v61, v122, v133
	v_fma_f32 v63, -v125, v61, v240
	v_fmac_f32_e32 v244, v125, v60
	v_fmac_f32_e32 v63, v122, v60
	v_fmac_f32_e32 v244, v122, v61
	v_cvt_pk_bf16_f32 v62, v60, v61
	v_cvt_pk_bf16_f32 v60, v63, v244
	ds_write2_b32 v162, v60, v62 offset0:120 offset1:188
	v_fma_f32 v60, -v125, v244, v239
	v_fma_f32 v61, v125, v63, v243
	v_fmac_f32_e32 v60, v122, v63
	v_fmac_f32_e32 v61, v122, v244
	v_fma_f32 v63, -v125, v61, v238
	v_fmac_f32_e32 v242, v125, v60
	v_fmac_f32_e32 v63, v122, v60
	v_fmac_f32_e32 v242, v122, v61
	v_cvt_pk_bf16_f32 v62, v60, v61
	v_cvt_pk_bf16_f32 v60, v63, v242
	ds_write2_b32 v163, v60, v62 offset0:112 offset1:180
	v_fma_f32 v60, -v125, v242, v233
	v_fma_f32 v61, v125, v63, v237
	v_fmac_f32_e32 v60, v122, v63
	v_fmac_f32_e32 v61, v122, v242
	v_fma_f32 v63, -v125, v61, v232
	v_fmac_f32_e32 v236, v125, v60
	v_fmac_f32_e32 v63, v122, v60
	v_fmac_f32_e32 v236, v122, v61
	v_cvt_pk_bf16_f32 v62, v60, v61
	v_cvt_pk_bf16_f32 v60, v63, v236
	ds_write2_b32 v164, v60, v62 offset0:104 offset1:172
	v_fma_f32 v60, -v125, v236, v231
	v_fma_f32 v61, v125, v63, v235
	v_fmac_f32_e32 v60, v122, v63
	v_fmac_f32_e32 v61, v122, v236
	v_fma_f32 v63, -v125, v61, v230
	v_fmac_f32_e32 v234, v125, v60
	v_fmac_f32_e32 v63, v122, v60
	v_fmac_f32_e32 v234, v122, v61
	v_cvt_pk_bf16_f32 v62, v60, v61
	v_cvt_pk_bf16_f32 v60, v63, v234
	ds_write2_b32 v165, v60, v62 offset0:96 offset1:164
	v_fma_f32 v60, -v125, v234, v225
	v_fma_f32 v61, v125, v63, v229
	v_fmac_f32_e32 v60, v122, v63
	v_fmac_f32_e32 v61, v122, v234
	v_fma_f32 v63, -v125, v61, v224
	v_fmac_f32_e32 v228, v125, v60
	v_fmac_f32_e32 v63, v122, v60
	v_fmac_f32_e32 v228, v122, v61
	v_cvt_pk_bf16_f32 v62, v60, v61
	v_cvt_pk_bf16_f32 v60, v63, v228
	ds_write2_b32 v166, v60, v62 offset0:88 offset1:156
	v_fma_f32 v60, -v125, v228, v223
	v_fma_f32 v61, v125, v63, v227
	v_fmac_f32_e32 v60, v122, v63
	v_fmac_f32_e32 v61, v122, v228
	v_fma_f32 v63, -v125, v61, v222
	v_fmac_f32_e32 v226, v125, v60
	v_fmac_f32_e32 v63, v122, v60
	v_fmac_f32_e32 v226, v122, v61
	v_cvt_pk_bf16_f32 v62, v60, v61
	v_cvt_pk_bf16_f32 v60, v63, v226
	ds_write2_b32 v167, v60, v62 offset0:80 offset1:148
	v_fma_f32 v60, -v125, v226, v217
	v_fma_f32 v61, v125, v63, v221
	v_fmac_f32_e32 v60, v122, v63
	v_fmac_f32_e32 v61, v122, v226
	v_fma_f32 v63, -v125, v61, v216
	v_fmac_f32_e32 v220, v125, v60
	v_fmac_f32_e32 v63, v122, v60
	v_fmac_f32_e32 v220, v122, v61
	v_cvt_pk_bf16_f32 v62, v60, v61
	v_cvt_pk_bf16_f32 v60, v63, v220
	ds_write2_b32 v168, v60, v62 offset0:72 offset1:140
	v_fma_f32 v60, -v125, v220, v215
	v_fma_f32 v61, v125, v63, v219
	v_fmac_f32_e32 v60, v122, v63
	v_fmac_f32_e32 v61, v122, v220
	v_fma_f32 v63, -v125, v61, v214
	v_fmac_f32_e32 v218, v125, v60
	v_fmac_f32_e32 v63, v122, v60
	v_fmac_f32_e32 v218, v122, v61
	v_cvt_pk_bf16_f32 v62, v60, v61
	v_cvt_pk_bf16_f32 v60, v63, v218
	ds_write2_b32 v169, v60, v62 offset0:64 offset1:132
	v_mov_b32_e32 v132, v63
	v_mov_b32_e32 v133, v218
	v_mfma_f32_16x16x32_bf16 v[214:217], v[48:51], v[178:181], 0
	v_mfma_f32_16x16x32_bf16 v[222:225], v[48:51], v[186:189], 0
	v_mfma_f32_16x16x32_bf16 v[230:233], v[48:51], v[194:197], 0
	v_mfma_f32_16x16x32_bf16 v[238:241], v[48:51], v[202:205], 0
	v_mfma_f32_16x16x32_bf16 v[218:221], v[48:51], v[182:185], 0
	v_mfma_f32_16x16x32_bf16 v[226:229], v[48:51], v[190:193], 0
	v_mfma_f32_16x16x32_bf16 v[234:237], v[48:51], v[198:201], 0
	v_mfma_f32_16x16x32_bf16 v[242:245], v[48:51], v[206:209], 0
	v_cvt_pk_bf16_f32 v56, v56, v57
	v_cvt_pk_bf16_f32 v57, v58, v59
	v_lshl_add_u64 v[62:63], s[98:99], 0, v[248:249]
	global_store_dwordx2 v[62:63], v[56:57], off
	ds_read_b128 v[56:59], v148 offset:8448
	ds_read_b128 v[60:63], v148 offset:8512
	ds_read_b128 v[64:67], v148 offset:8576
	ds_read_b128 v[68:71], v148 offset:8640
	v_permlane32_swap_b32_e32 v214, v230
	v_permlane32_swap_b32_e32 v222, v238
	v_permlane32_swap_b32_e32 v215, v231
	v_permlane32_swap_b32_e32 v223, v239
	v_permlane32_swap_b32_e32 v216, v232
	v_permlane32_swap_b32_e32 v224, v240
	v_permlane32_swap_b32_e32 v217, v233
	v_permlane32_swap_b32_e32 v225, v241
	v_permlane16_swap_b32_e32 v214, v222
	v_permlane16_swap_b32_e32 v230, v238
	v_permlane16_swap_b32_e32 v215, v223
	v_permlane16_swap_b32_e32 v231, v239
	v_permlane16_swap_b32_e32 v216, v224
	v_permlane16_swap_b32_e32 v232, v240
	v_permlane16_swap_b32_e32 v217, v225
	v_permlane16_swap_b32_e32 v233, v241
	v_permlane32_swap_b32_e32 v218, v234
	v_permlane32_swap_b32_e32 v226, v242
	v_permlane32_swap_b32_e32 v219, v235
	v_permlane32_swap_b32_e32 v227, v243
	v_permlane32_swap_b32_e32 v220, v236
	v_permlane32_swap_b32_e32 v228, v244
	v_permlane32_swap_b32_e32 v221, v237
	v_permlane32_swap_b32_e32 v229, v245
	v_permlane16_swap_b32_e32 v218, v226
	v_permlane16_swap_b32_e32 v234, v242
	v_permlane16_swap_b32_e32 v219, v227
	v_permlane16_swap_b32_e32 v235, v243
	v_permlane16_swap_b32_e32 v220, v228
	v_permlane16_swap_b32_e32 v236, v244
	v_permlane16_swap_b32_e32 v221, v229
	v_permlane16_swap_b32_e32 v237, v245
	s_waitcnt vmcnt(1)
	v_mov_b32_e32 v48, v52
	v_mov_b32_e32 v49, v53
	v_mov_b32_e32 v50, v54
	v_mov_b32_e32 v51, v55
	v_lshl_add_u64 v[170:171], s[98:99], 0, v[246:247]
	global_load_dwordx4 v[52:55], v[170:171], off
	s_sub_u32 s98, s98, 0x8000
	s_subb_u32 s99, s99, 0
	s_add_i32 s100, s100, 1
	s_cmp_lg_u32 s100, 0x10d
	s_cbranch_scc1 .Ls5f_bwd_loop
	s_waitcnt vmcnt(0)
	s_mov_b32 s25, 0x10d
	s_add_u32 s0, s58, 48
	s_addc_u32 s1, s59, 0
	s_branch .LBB0_414

; #define LAS __attribute__((address_space(3)))
; DI unsigned pk2(float lo, float hi) { f32x2 v = {lo, hi}; bf16x2_t b = __builtin_convertvector(v, bf16x2_t); return __builtin_bit_cast(unsigned, b); }
; #define MFMA16(a, b, c) __builtin_amdgcn_mfma_f32_16x16x32_bf16((a), (b), (c), 0, 0, 0)
; #define S5_CB() asm volatile("" ::: "memory")
; DI void s5_phase(const KArgs& a, int zz, int o, const bf16_t* H, bf16_t* YF, bf16_t* YB, LAS unsigned char* lds, int G, int bid, int wave, int lane) {
;     ...
;         auto iter = [&](const int ci, const bool do_c) __attribute__((always_inline)) {
;             const size_t row0 = chunk_row(ci);
;             const u32x4 u3 = loadu(ci + 3);
;             f32x2 bu[16];
; #pragma unroll
;             for (int s = 0; s < 16; ++s) { const int tt = DIRC ? 15 - s : s; bu[s] = *(const LAS f32x2*)(BU + tt * 132 + 2 * lane); }
;             bf16x8 Ax[4];
;             if (do_c) {
; #pragma unroll
;                 for (int kb = 0; kb < 4; ++kb) Ax[kb] = *(const LAS bf16x8*)(XS + fr * 68 + kb * 16 + fq * 4); }
;             S5_CB();
;             stageA(u1);
;             S5_CB();
; #pragma unroll
;             for (int s = 0; s < 16; ++s) { const int tt = DIRC ? 15 - s : s;
;                 const float nr = __builtin_fmaf(abr, xr, __builtin_fmaf(nabi, xi, bu[s][0])); const float ni = __builtin_fmaf(abr, xi, __builtin_fmaf(abi, xr, bu[s][1])); xr = nr; xi = ni;
;                 XS[tt * 68 + lane] = pk2(xr, xi); }
;             if (do_c) {
;                 f32x4 ya = (f32x4){0.f, 0.f, 0.f, 0.f};
; #pragma unroll
;                 for (int kb = 0; kb < 4; ++kb) ya = MFMA16(Cb[kb], Ax[kb], ya);
;                 u32x2 w; w.x = pk2(ya[0], ya[1]); w.y = pk2(ya[2], ya[3]); *(u32x2*)(Y + (rowprev + fr) * D + g * 16 + fq * 4) = w; }
;             S5_CB();
;             rowprev = row0; u1 = u2; u2 = u3;
;         };
;         iter(0, false);
;         for (int ci = 1; ci < 272; ++ci) iter(ci, true);
.Ls5f_fwd_entry:
	s_add_u32 s98, s56, 64
	s_addc_u32 s99, s57, 0
	s_mov_b32 s100, 0xfffe0000
	s_mov_b32 s101, -1
	s_lshl_b64 s[98:99], s[98:99], 11
	v_lshlrev_b64 v[56:57], 11, v[104:105]
	v_lshl_add_u64 v[246:247], v[126:127], 0, v[56:57]
	v_lshl_add_u64 v[248:249], v[128:129], 0, v[56:57]
	v_lshl_add_u64 v[248:249], v[248:249], 0, s[100:101]
	s_mov_b32 s100, 17
	ds_read_b128 v[56:59], v132 offset:8448
	ds_read_b128 v[60:63], v132 offset:8512
	ds_read_b128 v[64:67], v132 offset:8576
	ds_read_b128 v[68:71], v132 offset:8640
.Ls5f_fwd_loop:
	s_waitcnt lgkmcnt(0)
	v_mfma_f32_16x16x32_bf16 v[56:59], v[32:35], v[56:59], 0
	v_mfma_f32_16x16x32_bf16 v[56:59], v[36:39], v[60:63], v[56:59]
	v_mfma_f32_16x16x32_bf16 v[56:59], v[40:43], v[64:67], v[56:59]
	v_mfma_f32_16x16x32_bf16 v[56:59], v[44:47], v[68:71], v[56:59]
	v_fma_f32 v60, -v125, v131, v214
	v_fma_f32 v61, v125, v130, v218
	v_fmac_f32_e32 v60, v122, v130
	v_fmac_f32_e32 v61, v122, v131
	v_fma_f32 v63, -v125, v61, v215
	v_fmac_f32_e32 v219, v125, v60
	v_fmac_f32_e32 v63, v122, v60
	v_fmac_f32_e32 v219, v122, v61
	v_cvt_pk_bf16_f32 v62, v60, v61
	v_cvt_pk_bf16_f32 v60, v63, v219
	ds_write2_b32 v169, v62, v60 offset0:64 offset1:132
	v_fma_f32 v60, -v125, v219, v216
	v_fma_f32 v61, v125, v63, v220
	v_fmac_f32_e32 v60, v122, v63
	v_fmac_f32_e32 v61, v122, v219
	v_fma_f32 v63, -v125, v61, v217
	v_fmac_f32_e32 v221, v125, v60
	v_fmac_f32_e32 v63, v122, v60
	v_fmac_f32_e32 v221, v122, v61
	v_cvt_pk_bf16_f32 v62, v60, v61
	v_cvt_pk_bf16_f32 v60, v63, v221
	ds_write2_b32 v168, v62, v60 offset0:72 offset1:140
	v_fma_f32 v60, -v125, v221, v222
	v_fma_f32 v61, v125, v63, v226
	v_fmac_f32_e32 v60, v122, v63
	v_fmac_f32_e32 v61, v122, v221
	v_fma_f32 v63, -v125, v61, v223
	v_fmac_f32_e32 v227, v125, v60
	v_fmac_f32_e32 v63, v122, v60
	v_fmac_f32_e32 v227, v122, v61
	v_cvt_pk_bf16_f32 v62, v60, v61
	v_cvt_pk_bf16_f32 v60, v63, v227
	ds_write2_b32 v167, v62, v60 offset0:80 offset1:148
	v_fma_f32 v60, -v125, v227, v224
	v_fma_f32 v61, v125, v63, v228
	v_fmac_f32_e32 v60, v122, v63
	v_fmac_f32_e32 v61, v122, v227
	v_fma_f32 v63, -v125, v61, v225
	v_fmac_f32_e32 v229, v125, v60
	v_fmac_f32_e32 v63, v122, v60
	v_fmac_f32_e32 v229, v122, v61
	v_cvt_pk_bf16_f32 v62, v60, v61
	v_cvt_pk_bf16_f32 v60, v63, v229
	ds_write2_b32 v166, v62, v60 offset0:88 offset1:156
	v_fma_f32 v60, -v125, v229, v230
	v_fma_f32 v61, v125, v63, v234
	v_fmac_f32_e32 v60, v122, v63
	v_fmac_f32_e32 v61, v122, v229
	v_fma_f32 v63, -v125, v61, v231
	v_fmac_f32_e32 v235, v125, v60
	v_fmac_f32_e32 v63, v122, v60
	v_fmac_f32_e32 v235, v122, v61
	v_cvt_pk_bf16_f32 v62, v60, v61
	v_cvt_pk_bf16_f32 v60, v63, v235
	ds_write2_b32 v165, v62, v60 offset0:96 offset1:164
	v_fma_f32 v60, -v125, v235, v232
	v_fma_f32 v61, v125, v63, v236
	v_fmac_f32_e32 v60, v122, v63
	v_fmac_f32_e32 v61, v122, v235
	v_fma_f32 v63, -v125, v61, v233
	v_fmac_f32_e32 v237, v125, v60
	v_fmac_f32_e32 v63, v122, v60
	v_fmac_f32_e32 v237, v122, v61
	v_cvt_pk_bf16_f32 v62, v60, v61
	v_cvt_pk_bf16_f32 v60, v63, v237
	ds_write2_b32 v164, v62, v60 offset0:104 offset1:172
	v_fma_f32 v60, -v125, v237, v238
	v_fma_f32 v61, v125, v63, v242
	v_fmac_f32_e32 v60, v122, v63
	v_fmac_f32_e32 v61, v122, v237
	v_fma_f32 v63, -v125, v61, v239
	v_fmac_f32_e32 v243, v125, v60
	v_fmac_f32_e32 v63, v122, v60
	v_fmac_f32_e32 v243, v122, v61
	v_cvt_pk_bf16_f32 v62, v60, v61
	v_cvt_pk_bf16_f32 v60, v63, v243
	ds_write2_b32 v163, v62, v60 offset0:112 offset1:180
	v_fma_f32 v60, -v125, v243, v240
	v_fma_f32 v61, v125, v63, v244
	v_fmac_f32_e32 v60, v122, v63
	v_fmac_f32_e32 v61, v122, v243
	v_fma_f32 v63, -v125, v61, v241
	v_fmac_f32_e32 v245, v125, v60
	v_fmac_f32_e32 v63, v122, v60
	v_fmac_f32_e32 v245, v122, v61
	v_cvt_pk_bf16_f32 v62, v60, v61
	v_cvt_pk_bf16_f32 v60, v63, v245
	ds_write2_b32 v162, v62, v60 offset0:120 offset1:188
	v_mov_b32_e32 v130, v63
	v_mov_b32_e32 v131, v245
	v_mfma_f32_16x16x32_bf16 v[214:217], v[48:51], v[178:181], 0
	v_mfma_f32_16x16x32_bf16 v[222:225], v[48:51], v[186:189], 0
	v_mfma_f32_16x16x32_bf16 v[230:233], v[48:51], v[194:197], 0
	v_mfma_f32_16x16x32_bf16 v[238:241], v[48:51], v[202:205], 0
	v_mfma_f32_16x16x32_bf16 v[218:221], v[48:51], v[182:185], 0
	v_mfma_f32_16x16x32_bf16 v[226:229], v[48:51], v[190:193], 0
	v_mfma_f32_16x16x32_bf16 v[234:237], v[48:51], v[198:201], 0
	v_mfma_f32_16x16x32_bf16 v[242:245], v[48:51], v[206:209], 0
	v_cvt_pk_bf16_f32 v56, v56, v57
	v_cvt_pk_bf16_f32 v57, v58, v59
	v_lshl_add_u64 v[62:63], s[98:99], 0, v[248:249]
	global_store_dwordx2 v[62:63], v[56:57], off
	ds_read_b128 v[56:59], v132 offset:8448
	ds_read_b128 v[60:63], v132 offset:8512
	ds_read_b128 v[64:67], v132 offset:8576
	ds_read_b128 v[68:71], v132 offset:8640
	v_permlane32_swap_b32_e32 v214, v230
	v_permlane32_swap_b32_e32 v222, v238
	v_permlane32_swap_b32_e32 v215, v231
	v_permlane32_swap_b32_e32 v223, v239
	v_permlane32_swap_b32_e32 v216, v232
	v_permlane32_swap_b32_e32 v224, v240
	v_permlane32_swap_b32_e32 v217, v233
	v_permlane32_swap_b32_e32 v225, v241
	v_permlane16_swap_b32_e32 v214, v222
	v_permlane16_swap_b32_e32 v230, v238
	v_permlane16_swap_b32_e32 v215, v223
	v_permlane16_swap_b32_e32 v231, v239
	v_permlane16_swap_b32_e32 v216, v224
	v_permlane16_swap_b32_e32 v232, v240
	v_permlane16_swap_b32_e32 v217, v225
	v_permlane16_swap_b32_e32 v233, v241
	v_permlane32_swap_b32_e32 v218, v234
	v_permlane32_swap_b32_e32 v226, v242
	v_permlane32_swap_b32_e32 v219, v235
	v_permlane32_swap_b32_e32 v227, v243
	v_permlane32_swap_b32_e32 v220, v236
	v_permlane32_swap_b32_e32 v228, v244
	v_permlane32_swap_b32_e32 v221, v237
	v_permlane32_swap_b32_e32 v229, v245
	v_permlane16_swap_b32_e32 v218, v226
	v_permlane16_swap_b32_e32 v234, v242
	v_permlane16_swap_b32_e32 v219, v227
	v_permlane16_swap_b32_e32 v235, v243
	v_permlane16_swap_b32_e32 v220, v228
	v_permlane16_swap_b32_e32 v236, v244
	v_permlane16_swap_b32_e32 v221, v229
	v_permlane16_swap_b32_e32 v237, v245
	s_waitcnt vmcnt(1)
	v_mov_b32_e32 v48, v52
	v_mov_b32_e32 v49, v53
	v_mov_b32_e32 v50, v54
	v_mov_b32_e32 v51, v55
	v_lshl_add_u64 v[170:171], s[98:99], 0, v[246:247]
	global_load_dwordx4 v[52:55], v[170:171], off
	s_add_u32 s98, s98, 0x8000
	s_addc_u32 s99, s99, 0
	s_add_i32 s100, s100, 1
	s_cmp_lg_u32 s100, 0x10d
	s_cbranch_scc1 .Ls5f_fwd_loop
	s_waitcnt vmcnt(0)
	s_mov_b32 s23, 0x10d
	s_mov_b32 s24, 0x110d0
	s_add_u32 s0, s56, 0xfc0
	s_addc_u32 s1, s57, 0
	s_branch .LBB0_417
